# write-through (sc1) on the write-once 16-byte f32 output stores of the in-projection and out-projection epilogues, so they do not stay dirty in L2
# baseline (speedup 1.0000x reference)
; __device__ __forceinline__ void store_f32(const Acc& acc, float* base, int ld, int rl0, int cl0, int valid) {
; #pragma unroll
;     for (int ai = 0; ai < 2; ++ai)
; #pragma unroll
;         for (int m = 0; m < 4; ++m) { const int row = rl0 + ai * HALF + m * 16; if (row < valid) { float* rp = base + (size_t)row * ld + cl0;
; #pragma unroll
;             for (int bj = 0; bj < 2; ++bj)
; #pragma unroll
;                 for (int n = 0; n < 2; ++n) *(f32x4*)(rp + bj * HALF + n * 16) = acc[ai][bj][m][n]; } }
; }
.LBB0_281:
	v_lshl_add_u64 v[164:165], v[156:157], 2, s[94:95]
	v_cmp_gt_i32_e32 vcc, s9, v152
	s_and_saveexec_b64 s[6:7], vcc
	s_cbranch_execz .LBB0_283
	v_mad_i64_i32 v[154:155], s[24:25], s96, v152, 0
	v_lshl_add_u64 v[154:155], v[154:155], 2, v[164:165]
	global_store_dwordx4 v[154:155], v[30:33], off sc1
	global_store_dwordx4 v[154:155], v[126:129], off offset:64 sc1
	global_store_dwordx4 v[154:155], v[122:125], off offset:512 sc1
	global_store_dwordx4 v[154:155], v[118:121], off offset:576 sc1
.LBB0_283:
	s_or_b64 exec, exec, s[6:7]
	v_add_u32_e32 v162, 16, v152
	v_cmp_gt_i32_e32 vcc, s9, v162
	s_and_saveexec_b64 s[6:7], vcc
	s_cbranch_execz .LBB0_285
	v_mad_i64_i32 v[154:155], s[24:25], s96, v162, 0
	v_lshl_add_u64 v[154:155], v[154:155], 2, v[164:165]
	global_store_dwordx4 v[154:155], v[26:29], off sc1
	global_store_dwordx4 v[154:155], v[114:117], off offset:64 sc1
	global_store_dwordx4 v[154:155], v[110:113], off offset:512 sc1
	global_store_dwordx4 v[154:155], v[106:109], off offset:576 sc1
.LBB0_285:
	s_or_b64 exec, exec, s[6:7]
	v_add_u32_e32 v160, 32, v152
	v_cmp_gt_i32_e32 vcc, s9, v160
	s_and_saveexec_b64 s[6:7], vcc
	v_readlane_b32 s95, v254, 9
	s_cbranch_execz .LBB0_287
	v_mad_i64_i32 v[154:155], s[24:25], s96, v160, 0
	v_lshl_add_u64 v[154:155], v[154:155], 2, v[164:165]
	global_store_dwordx4 v[154:155], v[22:25], off sc1
	global_store_dwordx4 v[154:155], v[102:105], off offset:64 sc1
	global_store_dwordx4 v[154:155], v[98:101], off offset:512 sc1
	global_store_dwordx4 v[154:155], v[94:97], off offset:576 sc1
.LBB0_287:
	s_or_b64 exec, exec, s[6:7]
	v_add_u32_e32 v158, 48, v152
	v_cmp_gt_i32_e32 vcc, s9, v158
	s_and_saveexec_b64 s[6:7], vcc
	s_cbranch_execz .LBB0_289
	v_mad_i64_i32 v[154:155], s[24:25], s96, v158, 0
	v_lshl_add_u64 v[154:155], v[154:155], 2, v[164:165]
	global_store_dwordx4 v[154:155], v[18:21], off sc1
	global_store_dwordx4 v[154:155], v[90:93], off offset:64 sc1
	global_store_dwordx4 v[154:155], v[86:89], off offset:512 sc1
	global_store_dwordx4 v[154:155], v[82:85], off offset:576 sc1
.LBB0_289:
	s_or_b64 exec, exec, s[6:7]
	v_add_u32_e32 v154, 0x80, v152
	v_cmp_gt_i32_e32 vcc, s9, v154
	s_and_saveexec_b64 s[6:7], vcc
	s_cbranch_execz .LBB0_291
	v_mad_i64_i32 v[182:183], s[24:25], s96, v154, 0
	v_lshl_add_u64 v[182:183], v[182:183], 2, v[164:165]
	global_store_dwordx4 v[182:183], v[14:17], off sc1
	global_store_dwordx4 v[182:183], v[78:81], off offset:64 sc1
	global_store_dwordx4 v[182:183], v[74:77], off offset:512 sc1
	global_store_dwordx4 v[182:183], v[70:73], off offset:576 sc1
.LBB0_291:
	s_or_b64 exec, exec, s[6:7]
	v_add_u32_e32 v153, 0x90, v152
	v_cmp_gt_i32_e32 vcc, s9, v153
	s_and_saveexec_b64 s[6:7], vcc
	s_cbranch_execz .LBB0_293
	v_mad_i64_i32 v[182:183], s[24:25], s96, v153, 0
	v_lshl_add_u64 v[182:183], v[182:183], 2, v[164:165]
	global_store_dwordx4 v[182:183], v[10:13], off sc1
	global_store_dwordx4 v[182:183], v[66:69], off offset:64 sc1
	global_store_dwordx4 v[182:183], v[62:65], off offset:512 sc1
	global_store_dwordx4 v[182:183], v[58:61], off offset:576 sc1
.LBB0_293:
	s_or_b64 exec, exec, s[6:7]
	v_add_u32_e32 v151, 0xa0, v152
	v_cmp_gt_i32_e32 vcc, s9, v151
	s_and_saveexec_b64 s[6:7], vcc
	s_cbranch_execz .LBB0_295
	v_mad_i64_i32 v[182:183], s[24:25], s96, v151, 0
	v_lshl_add_u64 v[182:183], v[182:183], 2, v[164:165]
	global_store_dwordx4 v[182:183], v[6:9], off sc1
	global_store_dwordx4 v[182:183], v[54:57], off offset:64 sc1
	global_store_dwordx4 v[182:183], v[50:53], off offset:512 sc1
	global_store_dwordx4 v[182:183], v[46:49], off offset:576 sc1
.LBB0_295:
	s_or_b64 exec, exec, s[6:7]
	v_add_u32_e32 v134, 0xb0, v152
	v_cmp_gt_i32_e32 vcc, s9, v134
	s_and_saveexec_b64 s[6:7], vcc
	s_cbranch_execz .LBB0_297
	v_mad_i64_i32 v[182:183], s[24:25], s96, v134, 0
	v_lshl_add_u64 v[164:165], v[182:183], 2, v[164:165]
	global_store_dwordx4 v[164:165], v[2:5], off sc1
	global_store_dwordx4 v[164:165], v[42:45], off offset:64 sc1
	global_store_dwordx4 v[164:165], v[38:41], off offset:512 sc1
	global_store_dwordx4 v[164:165], v[34:37], off offset:576 sc1

; __device__ __forceinline__ void store_f32(const Acc& acc, float* base, int ld, int rl0, int cl0, int valid) {
; #pragma unroll
;     for (int ai = 0; ai < 2; ++ai)
; #pragma unroll
;         for (int m = 0; m < 4; ++m) { const int row = rl0 + ai * HALF + m * 16; if (row < valid) { float* rp = base + (size_t)row * ld + cl0;
; #pragma unroll
;             for (int bj = 0; bj < 2; ++bj)
; #pragma unroll
;                 for (int n = 0; n < 2; ++n) *(f32x4*)(rp + bj * HALF + n * 16) = acc[ai][bj][m][n]; } }
; }
.LBB0_309:
	s_addk_i32 s8, 0xee00
	v_add_u32_e32 v156, s8, v156
	v_ashrrev_i32_e32 v157, 31, v156
	v_cmp_ne_u64_e32 vcc, 0, v[164:165]
	s_and_saveexec_b64 s[8:9], vcc
	s_cbranch_execz .LBB0_311
	v_lshl_add_u64 v[164:165], v[156:157], 2, v[164:165]
	global_store_dwordx4 v[164:165], v[30:33], off sc1
	global_store_dwordx4 v[164:165], v[126:129], off offset:64 sc1
	global_store_dwordx4 v[164:165], v[122:125], off offset:512 sc1
	global_store_dwordx4 v[164:165], v[118:121], off offset:576 sc1

; __device__ __forceinline__ void store_f32(const Acc& acc, float* base, int ld, int rl0, int cl0, int valid) {
; #pragma unroll
;     for (int ai = 0; ai < 2; ++ai)
; #pragma unroll
;         for (int m = 0; m < 4; ++m) { const int row = rl0 + ai * HALF + m * 16; if (row < valid) { float* rp = base + (size_t)row * ld + cl0;
; #pragma unroll
;             for (int bj = 0; bj < 2; ++bj)
; #pragma unroll
;                 for (int n = 0; n < 2; ++n) *(f32x4*)(rp + bj * HALF + n * 16) = acc[ai][bj][m][n]; } }
; }
.LBB0_316:
	v_lshl_add_u64 v[118:119], v[156:157], 2, v[118:119]
	global_store_dwordx4 v[118:119], v[26:29], off sc1
	global_store_dwordx4 v[118:119], v[114:117], off offset:64 sc1
	global_store_dwordx4 v[118:119], v[110:113], off offset:512 sc1
	global_store_dwordx4 v[118:119], v[106:109], off offset:576 sc1

; __device__ __forceinline__ void store_f32(const Acc& acc, float* base, int ld, int rl0, int cl0, int valid) {
; #pragma unroll
;     for (int ai = 0; ai < 2; ++ai)
; #pragma unroll
;         for (int m = 0; m < 4; ++m) { const int row = rl0 + ai * HALF + m * 16; if (row < valid) { float* rp = base + (size_t)row * ld + cl0;
; #pragma unroll
;             for (int bj = 0; bj < 2; ++bj)
; #pragma unroll
;                 for (int n = 0; n < 2; ++n) *(f32x4*)(rp + bj * HALF + n * 16) = acc[ai][bj][m][n]; } }
; }
.LBB0_322:
	v_lshl_add_u64 v[106:107], v[156:157], 2, v[106:107]
	global_store_dwordx4 v[106:107], v[22:25], off sc1
	global_store_dwordx4 v[106:107], v[102:105], off offset:64 sc1
	global_store_dwordx4 v[106:107], v[98:101], off offset:512 sc1
	global_store_dwordx4 v[106:107], v[94:97], off offset:576 sc1

; __device__ __forceinline__ void store_f32(const Acc& acc, float* base, int ld, int rl0, int cl0, int valid) {
; #pragma unroll
;     for (int ai = 0; ai < 2; ++ai)
; #pragma unroll
;         for (int m = 0; m < 4; ++m) { const int row = rl0 + ai * HALF + m * 16; if (row < valid) { float* rp = base + (size_t)row * ld + cl0;
; #pragma unroll
;             for (int bj = 0; bj < 2; ++bj)
; #pragma unroll
;                 for (int n = 0; n < 2; ++n) *(f32x4*)(rp + bj * HALF + n * 16) = acc[ai][bj][m][n]; } }
; }
.LBB0_328:
	v_lshl_add_u64 v[94:95], v[156:157], 2, v[94:95]
	global_store_dwordx4 v[94:95], v[18:21], off sc1
	global_store_dwordx4 v[94:95], v[90:93], off offset:64 sc1
	global_store_dwordx4 v[94:95], v[86:89], off offset:512 sc1
	global_store_dwordx4 v[94:95], v[82:85], off offset:576 sc1

; __device__ __forceinline__ void store_f32(const Acc& acc, float* base, int ld, int rl0, int cl0, int valid) {
; #pragma unroll
;     for (int ai = 0; ai < 2; ++ai)
; #pragma unroll
;         for (int m = 0; m < 4; ++m) { const int row = rl0 + ai * HALF + m * 16; if (row < valid) { float* rp = base + (size_t)row * ld + cl0;
; #pragma unroll
;             for (int bj = 0; bj < 2; ++bj)
; #pragma unroll
;                 for (int n = 0; n < 2; ++n) *(f32x4*)(rp + bj * HALF + n * 16) = acc[ai][bj][m][n]; } }
; }
.LBB0_334:
	v_lshl_add_u64 v[82:83], v[156:157], 2, v[82:83]
	global_store_dwordx4 v[82:83], v[14:17], off sc1
	global_store_dwordx4 v[82:83], v[78:81], off offset:64 sc1
	global_store_dwordx4 v[82:83], v[74:77], off offset:512 sc1
	global_store_dwordx4 v[82:83], v[70:73], off offset:576 sc1

; __device__ __forceinline__ void store_f32(const Acc& acc, float* base, int ld, int rl0, int cl0, int valid) {
; #pragma unroll
;     for (int ai = 0; ai < 2; ++ai)
; #pragma unroll
;         for (int m = 0; m < 4; ++m) { const int row = rl0 + ai * HALF + m * 16; if (row < valid) { float* rp = base + (size_t)row * ld + cl0;
; #pragma unroll
;             for (int bj = 0; bj < 2; ++bj)
; #pragma unroll
;                 for (int n = 0; n < 2; ++n) *(f32x4*)(rp + bj * HALF + n * 16) = acc[ai][bj][m][n]; } }
; }
.LBB0_340:
	v_lshl_add_u64 v[70:71], v[156:157], 2, v[70:71]
	global_store_dwordx4 v[70:71], v[10:13], off sc1
	global_store_dwordx4 v[70:71], v[66:69], off offset:64 sc1
	global_store_dwordx4 v[70:71], v[62:65], off offset:512 sc1
	global_store_dwordx4 v[70:71], v[58:61], off offset:576 sc1

; __device__ __forceinline__ void store_f32(const Acc& acc, float* base, int ld, int rl0, int cl0, int valid) {
; #pragma unroll
;     for (int ai = 0; ai < 2; ++ai)
; #pragma unroll
;         for (int m = 0; m < 4; ++m) { const int row = rl0 + ai * HALF + m * 16; if (row < valid) { float* rp = base + (size_t)row * ld + cl0;
; #pragma unroll
;             for (int bj = 0; bj < 2; ++bj)
; #pragma unroll
;                 for (int n = 0; n < 2; ++n) *(f32x4*)(rp + bj * HALF + n * 16) = acc[ai][bj][m][n]; } }
; }
.LBB0_346:
	v_lshl_add_u64 v[58:59], v[156:157], 2, v[58:59]
	global_store_dwordx4 v[58:59], v[6:9], off sc1
	global_store_dwordx4 v[58:59], v[54:57], off offset:64 sc1
	global_store_dwordx4 v[58:59], v[50:53], off offset:512 sc1
	global_store_dwordx4 v[58:59], v[46:49], off offset:576 sc1

; __device__ __forceinline__ void store_f32(const Acc& acc, float* base, int ld, int rl0, int cl0, int valid) {
; #pragma unroll
;     for (int ai = 0; ai < 2; ++ai)
; #pragma unroll
;         for (int m = 0; m < 4; ++m) { const int row = rl0 + ai * HALF + m * 16; if (row < valid) { float* rp = base + (size_t)row * ld + cl0;
; #pragma unroll
;             for (int bj = 0; bj < 2; ++bj)
; #pragma unroll
;                 for (int n = 0; n < 2; ++n) *(f32x4*)(rp + bj * HALF + n * 16) = acc[ai][bj][m][n]; } }
; }
.LBB0_352:
	v_lshl_add_u64 v[46:47], v[156:157], 2, v[46:47]
	global_store_dwordx4 v[46:47], v[2:5], off sc1
	global_store_dwordx4 v[46:47], v[42:45], off offset:64 sc1
	global_store_dwordx4 v[46:47], v[38:41], off offset:512 sc1
	global_store_dwordx4 v[46:47], v[34:37], off offset:576 sc1

;     __device__ __forceinline__ void operator()(pg8::Acc& acc, const pg8::Unit& u, int wr, int wc, int fr, int fq) const {
;     ...
;         if (pn == 26 && wc == 0 && fq < 2) {
;             const f32x4 db = *(const f32x4*)(dtbias + 4 * fq);
; #pragma unroll
;             for (int ai = 0; ai < 2; ++ai)
; #pragma unroll
;                 for (int m = 0; m < 4; ++m) { const int row = rl0 + ai * 128 + m * 16; f32x4 v = acc[ai][0][m][0] + db;
; #pragma unroll
;                     for (int e = 0; e < 4; ++e) v[e] = (v[e] > 20.f) ? v[e] : log1pf(__expf(v[e]));
;                     *(f32x4*)(DT + (r0 + row) * 8 + 4 * fq) = v; }
;         }
.LBB0_361:
	s_or_b64 exec, exec, s[8:9]
	s_lshl_b64 s[8:9], s[34:35], 13
	v_readlane_b32 s23, v254, 21
	v_ashrrev_i32_e32 v153, 31, v152
	s_add_u32 s8, s23, s8
	v_readlane_b32 s23, v254, 22
	s_addc_u32 s9, s23, s9
	v_lshlrev_b64 v[38:39], 5, v[152:153]
	v_lshl_add_u64 v[38:39], s[8:9], 0, v[38:39]
	v_lshlrev_b32_e32 v134, 2, v136
	v_pk_add_f32 v[26:27], v[26:27], v[34:35]
	v_lshl_add_u64 v[38:39], v[38:39], 0, v[134:135]
	v_cmp_nlt_f32_e32 vcc, s33, v26
	global_store_dwordx4 v[38:39], v[30:33], off sc1
	s_and_saveexec_b64 s[34:35], vcc
	s_cbranch_execz .LBB0_363
	v_mul_f32_e32 v26, 0x3fb8aa3b, v26
	v_exp_f32_e32 v26, v26
	s_nop 0
	v_add_f32_e32 v32, 1.0, v26
	v_frexp_mant_f32_e32 v38, v32
	v_cvt_f64_f32_e32 v[30:31], v32
	v_frexp_exp_i32_f64_e32 v30, v[30:31]
	v_cmp_gt_f32_e32 vcc, s92, v38
	v_add_f32_e32 v33, -1.0, v32
	v_sub_f32_e32 v39, v33, v32
	v_subbrev_co_u32_e32 v42, vcc, 0, v30, vcc
	v_sub_u32_e32 v30, 0, v42
	v_sub_f32_e32 v33, v26, v33
	v_add_f32_e32 v39, 1.0, v39
	v_ldexp_f32 v31, v32, v30
	v_add_f32_e32 v33, v33, v39
	v_add_f32_e32 v32, -1.0, v31
	v_add_f32_e32 v38, 1.0, v31
	v_ldexp_f32 v30, v33, v30
	v_add_f32_e32 v33, 1.0, v32
	v_add_f32_e32 v39, -1.0, v38
	v_sub_f32_e32 v33, v31, v33
	v_sub_f32_e32 v31, v31, v39
	v_add_f32_e32 v33, v30, v33
	v_add_f32_e32 v30, v30, v31
	v_add_f32_e32 v43, v38, v30
	v_rcp_f32_e32 v45, v43
	v_sub_f32_e32 v31, v43, v38
	v_sub_f32_e32 v44, v30, v31
	v_add_f32_e32 v31, v32, v33
	v_mul_f32_e32 v47, v31, v45
	v_sub_f32_e32 v30, v31, v32
	v_mul_f32_e32 v32, v43, v47
	v_fma_f32 v38, v47, v43, -v32
	v_fmac_f32_e32 v38, v47, v44
	v_sub_f32_e32 v46, v33, v30
	v_add_f32_e32 v30, v32, v38
	v_sub_f32_e32 v33, v31, v30
	v_pk_add_f32 v[40:41], v[30:31], v[32:33] neg_lo:[0,1] neg_hi:[0,1]
	v_mov_b32_e32 v39, v30
	v_pk_add_f32 v[30:31], v[40:41], v[38:39] neg_lo:[0,1] neg_hi:[0,1]
	v_cmp_neq_f32_e32 vcc, s10, v26
	v_add_f32_e32 v31, v46, v31
	v_add_f32_e32 v30, v30, v31
	v_add_f32_e32 v31, v33, v30
	v_mul_f32_e32 v46, v45, v31
	v_mul_f32_e32 v32, v43, v46
	v_fma_f32 v38, v46, v43, -v32
	v_fmac_f32_e32 v38, v46, v44
	v_sub_f32_e32 v33, v33, v31
	v_add_f32_e32 v43, v30, v33
	v_add_f32_e32 v30, v32, v38
	v_sub_f32_e32 v33, v31, v30
	v_pk_add_f32 v[40:41], v[30:31], v[32:33] neg_lo:[0,1] neg_hi:[0,1]
	v_mov_b32_e32 v39, v30
	v_pk_add_f32 v[30:31], v[40:41], v[38:39] neg_lo:[0,1] neg_hi:[0,1]
	s_nop 0
	v_add_f32_e32 v31, v43, v31
	v_add_f32_e32 v30, v30, v31
	v_add_f32_e32 v31, v47, v46
	v_add_f32_e32 v30, v33, v30
	v_sub_f32_e32 v32, v31, v47
	v_mul_f32_e32 v30, v45, v30
	v_sub_f32_e32 v32, v46, v32
	v_add_f32_e32 v32, v32, v30
	v_add_f32_e32 v38, v31, v32
	v_mul_f32_e32 v39, v38, v38
	v_fmamk_f32 v30, v39, 0x3e9b6dac, v175
	v_fmaak_f32 v151, v39, v30, 0x3f2aaada
	v_cvt_f32_i32_e32 v30, v42
	v_sub_f32_e32 v31, v38, v31
	v_sub_f32_e32 v31, v32, v31
	v_ldexp_f32 v40, v31, 1
	v_mul_f32_e32 v31, v38, v39
	v_ldexp_f32 v33, v38, 1
	v_pk_mul_f32 v[38:39], v[30:31], v[150:151]
	s_nop 0
	v_fma_f32 v32, v30, s93, -v38
	v_fmac_f32_e32 v32, 0xb102e308, v30
	v_pk_add_f32 v[30:31], v[38:39], v[32:33]
	s_nop 0
	v_sub_f32_e32 v33, v31, v33
	v_sub_f32_e32 v33, v39, v33
	v_add_f32_e32 v41, v40, v33
	v_mov_b32_e32 v40, v38
	v_pk_add_f32 v[38:39], v[30:31], v[38:39] neg_lo:[0,1] neg_hi:[0,1]
	v_pk_add_f32 v[42:43], v[30:31], v[40:41]
	v_mov_b32_e32 v33, v30
	v_mov_b32_e32 v39, v43
	v_pk_add_f32 v[44:45], v[32:33], v[38:39] neg_lo:[0,1] neg_hi:[0,1]
	v_pk_add_f32 v[32:33], v[32:33], v[38:39]
	v_mov_b32_e32 v40, v41
	v_pk_add_f32 v[38:39], v[32:33], v[30:31] op_sel:[1,0] op_sel_hi:[0,1] neg_lo:[0,1] neg_hi:[0,1]
	v_pk_add_f32 v[46:47], v[42:43], v[38:39] op_sel_hi:[1,0] neg_lo:[0,1] neg_hi:[0,1]
	v_mov_b32_e32 v42, v43
	v_mov_b32_e32 v43, v33
	v_pk_mov_b32 v[38:39], v[30:31], v[38:39] op_sel:[1,0]
	v_mov_b32_e32 v41, v30
	v_pk_add_f32 v[38:39], v[42:43], v[38:39] neg_lo:[0,1] neg_hi:[0,1]
	v_mov_b32_e32 v46, v44
	v_pk_add_f32 v[30:31], v[40:41], v[38:39] neg_lo:[0,1] neg_hi:[0,1]
	v_mov_b32_e32 v45, v33
	v_pk_add_f32 v[38:39], v[46:47], v[30:31]
	s_nop 0
	v_pk_add_f32 v[40:41], v[38:39], v[38:39] op_sel:[0,1] op_sel_hi:[1,0]
	s_nop 0
	v_pk_add_f32 v[32:33], v[32:33], v[40:41] op_sel:[1,0] op_sel_hi:[0,1]
	v_mov_b32_e32 v39, v32
	v_pk_add_f32 v[42:43], v[38:39], v[44:45] neg_lo:[0,1] neg_hi:[0,1]
	v_mov_b32_e32 v31, v40
	v_sub_f32_e32 v33, v38, v42
	v_pk_add_f32 v[30:31], v[30:31], v[42:43] neg_lo:[0,1] neg_hi:[0,1]
	v_sub_f32_e32 v33, v44, v33
	v_add_f32_e32 v30, v30, v33
	v_add_f32_e32 v30, v30, v31
	v_add_f32_e32 v30, v32, v30
	v_cndmask_b32_e32 v30, v178, v30, vcc
	v_cmp_ngt_f32_e32 vcc, -1.0, v26
	s_nop 1
	v_cndmask_b32_e32 v30, v179, v30, vcc
	v_cmp_neq_f32_e32 vcc, -1.0, v26
	s_nop 1
	v_cndmask_b32_e32 v30, v180, v30, vcc
	v_cmp_lt_f32_e64 vcc, |v26|, s11
	s_nop 1
	v_cndmask_b32_e32 v26, v30, v26, vcc

;     __device__ __forceinline__ void operator()(pg8::Acc& acc, const pg8::Unit& u, int wr, int wc, int fr, int fq) const {
;     ...
;         if (pn == 26 && wc == 0 && fq < 2) {
;             const f32x4 db = *(const f32x4*)(dtbias + 4 * fq);
; #pragma unroll
;             for (int ai = 0; ai < 2; ++ai)
; #pragma unroll
;                 for (int m = 0; m < 4; ++m) { const int row = rl0 + ai * 128 + m * 16; f32x4 v = acc[ai][0][m][0] + db;
; #pragma unroll
;                     for (int e = 0; e < 4; ++e) v[e] = (v[e] > 20.f) ? v[e] : log1pf(__expf(v[e]));
;                     *(f32x4*)(DT + (r0 + row) * 8 + 4 * fq) = v; }
;         }
.LBB0_367:
	s_or_b64 exec, exec, s[34:35]
	v_lshlrev_b64 v[30:31], 5, v[162:163]
	v_lshl_add_u64 v[30:31], s[8:9], 0, v[30:31]
	v_pk_add_f32 v[22:23], v[22:23], v[34:35]
	v_lshl_add_u64 v[30:31], v[30:31], 0, v[134:135]
	v_cmp_nlt_f32_e32 vcc, s33, v22
	global_store_dwordx4 v[30:31], v[26:29], off sc1
	s_and_saveexec_b64 s[34:35], vcc
	s_cbranch_execz .LBB0_369
	v_mul_f32_e32 v22, 0x3fb8aa3b, v22
	v_exp_f32_e32 v22, v22
	s_nop 0
	v_add_f32_e32 v28, 1.0, v22
	v_frexp_mant_f32_e32 v30, v28
	v_cvt_f64_f32_e32 v[26:27], v28
	v_frexp_exp_i32_f64_e32 v26, v[26:27]
	v_cmp_gt_f32_e32 vcc, s92, v30
	v_add_f32_e32 v29, -1.0, v28
	v_sub_f32_e32 v31, v29, v28
	v_subbrev_co_u32_e32 v38, vcc, 0, v26, vcc
	v_sub_u32_e32 v26, 0, v38
	v_sub_f32_e32 v29, v22, v29
	v_add_f32_e32 v31, 1.0, v31
	v_ldexp_f32 v27, v28, v26
	v_add_f32_e32 v29, v29, v31
	v_add_f32_e32 v28, -1.0, v27
	v_add_f32_e32 v30, 1.0, v27
	v_ldexp_f32 v26, v29, v26
	v_add_f32_e32 v29, 1.0, v28
	v_add_f32_e32 v31, -1.0, v30
	v_sub_f32_e32 v29, v27, v29
	v_sub_f32_e32 v27, v27, v31
	v_add_f32_e32 v29, v26, v29
	v_add_f32_e32 v26, v26, v27
	v_add_f32_e32 v39, v30, v26
	v_rcp_f32_e32 v41, v39
	v_sub_f32_e32 v27, v39, v30
	v_sub_f32_e32 v40, v26, v27
	v_add_f32_e32 v27, v28, v29
	v_mul_f32_e32 v43, v27, v41
	v_sub_f32_e32 v26, v27, v28
	v_mul_f32_e32 v28, v39, v43
	v_fma_f32 v30, v43, v39, -v28
	v_fmac_f32_e32 v30, v43, v40
	v_sub_f32_e32 v42, v29, v26
	v_add_f32_e32 v26, v28, v30
	v_sub_f32_e32 v29, v27, v26
	v_pk_add_f32 v[32:33], v[26:27], v[28:29] neg_lo:[0,1] neg_hi:[0,1]
	v_mov_b32_e32 v31, v26
	v_pk_add_f32 v[26:27], v[32:33], v[30:31] neg_lo:[0,1] neg_hi:[0,1]
	v_cmp_neq_f32_e32 vcc, s10, v22
	v_add_f32_e32 v27, v42, v27
	v_add_f32_e32 v26, v26, v27
	v_add_f32_e32 v27, v29, v26
	v_mul_f32_e32 v42, v41, v27
	v_mul_f32_e32 v28, v39, v42
	v_fma_f32 v30, v42, v39, -v28
	v_fmac_f32_e32 v30, v42, v40
	v_sub_f32_e32 v29, v29, v27
	v_add_f32_e32 v39, v26, v29
	v_add_f32_e32 v26, v28, v30
	v_sub_f32_e32 v29, v27, v26
	v_pk_add_f32 v[32:33], v[26:27], v[28:29] neg_lo:[0,1] neg_hi:[0,1]
	v_mov_b32_e32 v31, v26
	v_pk_add_f32 v[26:27], v[32:33], v[30:31] neg_lo:[0,1] neg_hi:[0,1]
	s_nop 0
	v_add_f32_e32 v27, v39, v27
	v_add_f32_e32 v26, v26, v27
	v_add_f32_e32 v27, v43, v42
	v_add_f32_e32 v26, v29, v26
	v_sub_f32_e32 v28, v27, v43
	v_mul_f32_e32 v26, v41, v26
	v_sub_f32_e32 v28, v42, v28
	v_add_f32_e32 v28, v28, v26
	v_add_f32_e32 v30, v27, v28
	v_mul_f32_e32 v31, v30, v30
	v_fmamk_f32 v26, v31, 0x3e9b6dac, v175
	v_fmaak_f32 v151, v31, v26, 0x3f2aaada
	v_cvt_f32_i32_e32 v26, v38
	v_sub_f32_e32 v27, v30, v27
	v_sub_f32_e32 v27, v28, v27
	v_ldexp_f32 v32, v27, 1
	v_mul_f32_e32 v27, v30, v31
	v_ldexp_f32 v29, v30, 1
	v_pk_mul_f32 v[30:31], v[26:27], v[150:151]
	s_nop 0
	v_fma_f32 v28, v26, s93, -v30
	v_fmac_f32_e32 v28, 0xb102e308, v26
	v_pk_add_f32 v[26:27], v[30:31], v[28:29]
	s_nop 0
	v_sub_f32_e32 v29, v27, v29
	v_sub_f32_e32 v29, v31, v29
	v_add_f32_e32 v33, v32, v29
	v_mov_b32_e32 v32, v30
	v_pk_add_f32 v[30:31], v[26:27], v[30:31] neg_lo:[0,1] neg_hi:[0,1]
	v_pk_add_f32 v[38:39], v[26:27], v[32:33]
	v_mov_b32_e32 v29, v26
	v_mov_b32_e32 v31, v39
	v_pk_add_f32 v[40:41], v[28:29], v[30:31] neg_lo:[0,1] neg_hi:[0,1]
	v_pk_add_f32 v[28:29], v[28:29], v[30:31]
	v_mov_b32_e32 v32, v33
	v_pk_add_f32 v[30:31], v[28:29], v[26:27] op_sel:[1,0] op_sel_hi:[0,1] neg_lo:[0,1] neg_hi:[0,1]
	v_pk_add_f32 v[42:43], v[38:39], v[30:31] op_sel_hi:[1,0] neg_lo:[0,1] neg_hi:[0,1]
	v_mov_b32_e32 v38, v39
	v_mov_b32_e32 v39, v29
	v_pk_mov_b32 v[30:31], v[26:27], v[30:31] op_sel:[1,0]
	v_mov_b32_e32 v33, v26
	v_pk_add_f32 v[30:31], v[38:39], v[30:31] neg_lo:[0,1] neg_hi:[0,1]
	v_mov_b32_e32 v42, v40
	v_pk_add_f32 v[26:27], v[32:33], v[30:31] neg_lo:[0,1] neg_hi:[0,1]
	v_mov_b32_e32 v41, v29
	v_pk_add_f32 v[30:31], v[42:43], v[26:27]
	s_nop 0
	v_pk_add_f32 v[32:33], v[30:31], v[30:31] op_sel:[0,1] op_sel_hi:[1,0]
	s_nop 0
	v_pk_add_f32 v[28:29], v[28:29], v[32:33] op_sel:[1,0] op_sel_hi:[0,1]
	v_mov_b32_e32 v31, v28
	v_pk_add_f32 v[38:39], v[30:31], v[40:41] neg_lo:[0,1] neg_hi:[0,1]
	v_mov_b32_e32 v27, v32
	v_sub_f32_e32 v29, v30, v38
	v_pk_add_f32 v[26:27], v[26:27], v[38:39] neg_lo:[0,1] neg_hi:[0,1]
	v_sub_f32_e32 v29, v40, v29
	v_add_f32_e32 v26, v26, v29
	v_add_f32_e32 v26, v26, v27
	v_add_f32_e32 v26, v28, v26
	v_cndmask_b32_e32 v26, v178, v26, vcc
	v_cmp_ngt_f32_e32 vcc, -1.0, v22
	s_nop 1
	v_cndmask_b32_e32 v26, v179, v26, vcc
	v_cmp_neq_f32_e32 vcc, -1.0, v22
	s_nop 1
	v_cndmask_b32_e32 v26, v180, v26, vcc
	v_cmp_lt_f32_e64 vcc, |v22|, s11
	s_nop 1
	v_cndmask_b32_e32 v22, v26, v22, vcc

;     __device__ __forceinline__ void operator()(pg8::Acc& acc, const pg8::Unit& u, int wr, int wc, int fr, int fq) const {
;     ...
;         if (pn == 26 && wc == 0 && fq < 2) {
;             const f32x4 db = *(const f32x4*)(dtbias + 4 * fq);
; #pragma unroll
;             for (int ai = 0; ai < 2; ++ai)
; #pragma unroll
;                 for (int m = 0; m < 4; ++m) { const int row = rl0 + ai * 128 + m * 16; f32x4 v = acc[ai][0][m][0] + db;
; #pragma unroll
;                     for (int e = 0; e < 4; ++e) v[e] = (v[e] > 20.f) ? v[e] : log1pf(__expf(v[e]));
;                     *(f32x4*)(DT + (r0 + row) * 8 + 4 * fq) = v; }
;         }
.LBB0_373:
	s_or_b64 exec, exec, s[34:35]
	v_lshlrev_b64 v[26:27], 5, v[160:161]
	v_lshl_add_u64 v[26:27], s[8:9], 0, v[26:27]
	v_pk_add_f32 v[18:19], v[18:19], v[34:35]
	v_lshl_add_u64 v[26:27], v[26:27], 0, v[134:135]
	v_cmp_nlt_f32_e32 vcc, s33, v18
	global_store_dwordx4 v[26:27], v[22:25], off sc1
	s_and_saveexec_b64 s[34:35], vcc
	s_cbranch_execz .LBB0_375
	v_mul_f32_e32 v18, 0x3fb8aa3b, v18
	v_exp_f32_e32 v18, v18
	s_nop 0
	v_add_f32_e32 v24, 1.0, v18
	v_frexp_mant_f32_e32 v26, v24
	v_cvt_f64_f32_e32 v[22:23], v24
	v_frexp_exp_i32_f64_e32 v22, v[22:23]
	v_cmp_gt_f32_e32 vcc, s92, v26
	v_add_f32_e32 v25, -1.0, v24
	v_sub_f32_e32 v27, v25, v24
	v_subbrev_co_u32_e32 v30, vcc, 0, v22, vcc
	v_sub_u32_e32 v22, 0, v30
	v_sub_f32_e32 v25, v18, v25
	v_add_f32_e32 v27, 1.0, v27
	v_ldexp_f32 v23, v24, v22
	v_add_f32_e32 v25, v25, v27
	v_add_f32_e32 v24, -1.0, v23
	v_add_f32_e32 v26, 1.0, v23
	v_ldexp_f32 v22, v25, v22
	v_add_f32_e32 v25, 1.0, v24
	v_add_f32_e32 v27, -1.0, v26
	v_sub_f32_e32 v25, v23, v25
	v_sub_f32_e32 v23, v23, v27
	v_add_f32_e32 v25, v22, v25
	v_add_f32_e32 v22, v22, v23
	v_add_f32_e32 v31, v26, v22
	v_rcp_f32_e32 v33, v31
	v_sub_f32_e32 v23, v31, v26
	v_sub_f32_e32 v32, v22, v23
	v_add_f32_e32 v23, v24, v25
	v_mul_f32_e32 v39, v23, v33
	v_sub_f32_e32 v22, v23, v24
	v_mul_f32_e32 v24, v31, v39
	v_fma_f32 v26, v39, v31, -v24
	v_fmac_f32_e32 v26, v39, v32
	v_sub_f32_e32 v38, v25, v22
	v_add_f32_e32 v22, v24, v26
	v_sub_f32_e32 v25, v23, v22
	v_pk_add_f32 v[28:29], v[22:23], v[24:25] neg_lo:[0,1] neg_hi:[0,1]
	v_mov_b32_e32 v27, v22
	v_pk_add_f32 v[22:23], v[28:29], v[26:27] neg_lo:[0,1] neg_hi:[0,1]
	v_cmp_neq_f32_e32 vcc, s10, v18
	v_add_f32_e32 v23, v38, v23
	v_add_f32_e32 v22, v22, v23
	v_add_f32_e32 v23, v25, v22
	v_mul_f32_e32 v38, v33, v23
	v_mul_f32_e32 v24, v31, v38
	v_fma_f32 v26, v38, v31, -v24
	v_fmac_f32_e32 v26, v38, v32
	v_sub_f32_e32 v25, v25, v23
	v_add_f32_e32 v31, v22, v25
	v_add_f32_e32 v22, v24, v26
	v_sub_f32_e32 v25, v23, v22
	v_pk_add_f32 v[28:29], v[22:23], v[24:25] neg_lo:[0,1] neg_hi:[0,1]
	v_mov_b32_e32 v27, v22
	v_pk_add_f32 v[22:23], v[28:29], v[26:27] neg_lo:[0,1] neg_hi:[0,1]
	s_nop 0
	v_add_f32_e32 v23, v31, v23
	v_add_f32_e32 v22, v22, v23
	v_add_f32_e32 v23, v39, v38
	v_add_f32_e32 v22, v25, v22
	v_sub_f32_e32 v24, v23, v39
	v_mul_f32_e32 v22, v33, v22
	v_sub_f32_e32 v24, v38, v24
	v_add_f32_e32 v24, v24, v22
	v_add_f32_e32 v26, v23, v24
	v_mul_f32_e32 v27, v26, v26
	v_fmamk_f32 v22, v27, 0x3e9b6dac, v175
	v_fmaak_f32 v151, v27, v22, 0x3f2aaada
	v_cvt_f32_i32_e32 v22, v30
	v_sub_f32_e32 v23, v26, v23
	v_sub_f32_e32 v23, v24, v23
	v_ldexp_f32 v28, v23, 1
	v_mul_f32_e32 v23, v26, v27
	v_ldexp_f32 v25, v26, 1
	v_pk_mul_f32 v[26:27], v[22:23], v[150:151]
	s_nop 0
	v_fma_f32 v24, v22, s93, -v26
	v_fmac_f32_e32 v24, 0xb102e308, v22
	v_pk_add_f32 v[22:23], v[26:27], v[24:25]
	s_nop 0
	v_sub_f32_e32 v25, v23, v25
	v_sub_f32_e32 v25, v27, v25
	v_add_f32_e32 v29, v28, v25
	v_mov_b32_e32 v28, v26
	v_pk_add_f32 v[26:27], v[22:23], v[26:27] neg_lo:[0,1] neg_hi:[0,1]
	v_pk_add_f32 v[30:31], v[22:23], v[28:29]
	v_mov_b32_e32 v25, v22
	v_mov_b32_e32 v27, v31
	v_pk_add_f32 v[32:33], v[24:25], v[26:27] neg_lo:[0,1] neg_hi:[0,1]
	v_pk_add_f32 v[24:25], v[24:25], v[26:27]
	v_mov_b32_e32 v28, v29
	v_pk_add_f32 v[26:27], v[24:25], v[22:23] op_sel:[1,0] op_sel_hi:[0,1] neg_lo:[0,1] neg_hi:[0,1]
	v_pk_add_f32 v[38:39], v[30:31], v[26:27] op_sel_hi:[1,0] neg_lo:[0,1] neg_hi:[0,1]
	v_mov_b32_e32 v30, v31
	v_mov_b32_e32 v31, v25
	v_pk_mov_b32 v[26:27], v[22:23], v[26:27] op_sel:[1,0]
	v_mov_b32_e32 v29, v22
	v_pk_add_f32 v[26:27], v[30:31], v[26:27] neg_lo:[0,1] neg_hi:[0,1]
	v_mov_b32_e32 v38, v32
	v_pk_add_f32 v[22:23], v[28:29], v[26:27] neg_lo:[0,1] neg_hi:[0,1]
	v_mov_b32_e32 v33, v25
	v_pk_add_f32 v[26:27], v[38:39], v[22:23]
	s_nop 0
	v_pk_add_f32 v[28:29], v[26:27], v[26:27] op_sel:[0,1] op_sel_hi:[1,0]
	s_nop 0
	v_pk_add_f32 v[24:25], v[24:25], v[28:29] op_sel:[1,0] op_sel_hi:[0,1]
	v_mov_b32_e32 v27, v24
	v_pk_add_f32 v[30:31], v[26:27], v[32:33] neg_lo:[0,1] neg_hi:[0,1]
	v_mov_b32_e32 v23, v28
	v_sub_f32_e32 v25, v26, v30
	v_pk_add_f32 v[22:23], v[22:23], v[30:31] neg_lo:[0,1] neg_hi:[0,1]
	v_sub_f32_e32 v25, v32, v25
	v_add_f32_e32 v22, v22, v25
	v_add_f32_e32 v22, v22, v23
	v_add_f32_e32 v22, v24, v22
	v_cndmask_b32_e32 v22, v178, v22, vcc
	v_cmp_ngt_f32_e32 vcc, -1.0, v18
	s_nop 1
	v_cndmask_b32_e32 v22, v179, v22, vcc
	v_cmp_neq_f32_e32 vcc, -1.0, v18
	s_nop 1
	v_cndmask_b32_e32 v22, v180, v22, vcc
	v_cmp_lt_f32_e64 vcc, |v18|, s11
	s_nop 1
	v_cndmask_b32_e32 v18, v22, v18, vcc

;     __device__ __forceinline__ void operator()(pg8::Acc& acc, const pg8::Unit& u, int wr, int wc, int fr, int fq) const {
;     ...
;         if (pn == 26 && wc == 0 && fq < 2) {
;             const f32x4 db = *(const f32x4*)(dtbias + 4 * fq);
; #pragma unroll
;             for (int ai = 0; ai < 2; ++ai)
; #pragma unroll
;                 for (int m = 0; m < 4; ++m) { const int row = rl0 + ai * 128 + m * 16; f32x4 v = acc[ai][0][m][0] + db;
; #pragma unroll
;                     for (int e = 0; e < 4; ++e) v[e] = (v[e] > 20.f) ? v[e] : log1pf(__expf(v[e]));
;                     *(f32x4*)(DT + (r0 + row) * 8 + 4 * fq) = v; }
;         }
.LBB0_379:
	s_or_b64 exec, exec, s[34:35]
	v_lshlrev_b64 v[22:23], 5, v[158:159]
	v_lshl_add_u64 v[22:23], s[8:9], 0, v[22:23]
	v_pk_add_f32 v[14:15], v[14:15], v[34:35]
	v_lshl_add_u64 v[22:23], v[22:23], 0, v[134:135]
	v_cmp_nlt_f32_e32 vcc, s33, v14
	global_store_dwordx4 v[22:23], v[18:21], off sc1
	s_and_saveexec_b64 s[34:35], vcc
	s_cbranch_execz .LBB0_381
	v_mul_f32_e32 v14, 0x3fb8aa3b, v14
	v_exp_f32_e32 v14, v14
	s_nop 0
	v_add_f32_e32 v20, 1.0, v14
	v_frexp_mant_f32_e32 v22, v20
	v_cvt_f64_f32_e32 v[18:19], v20
	v_frexp_exp_i32_f64_e32 v18, v[18:19]
	v_cmp_gt_f32_e32 vcc, s92, v22
	v_add_f32_e32 v21, -1.0, v20
	v_sub_f32_e32 v23, v21, v20
	v_subbrev_co_u32_e32 v26, vcc, 0, v18, vcc
	v_sub_u32_e32 v18, 0, v26
	v_sub_f32_e32 v21, v14, v21
	v_add_f32_e32 v23, 1.0, v23
	v_ldexp_f32 v19, v20, v18
	v_add_f32_e32 v21, v21, v23
	v_add_f32_e32 v20, -1.0, v19
	v_add_f32_e32 v22, 1.0, v19
	v_ldexp_f32 v18, v21, v18
	v_add_f32_e32 v21, 1.0, v20
	v_add_f32_e32 v23, -1.0, v22
	v_sub_f32_e32 v21, v19, v21
	v_sub_f32_e32 v19, v19, v23
	v_add_f32_e32 v21, v18, v21
	v_add_f32_e32 v18, v18, v19
	v_add_f32_e32 v27, v22, v18
	v_rcp_f32_e32 v29, v27
	v_sub_f32_e32 v19, v27, v22
	v_sub_f32_e32 v28, v18, v19
	v_add_f32_e32 v19, v20, v21
	v_mul_f32_e32 v31, v19, v29
	v_sub_f32_e32 v18, v19, v20
	v_mul_f32_e32 v20, v27, v31
	v_fma_f32 v22, v31, v27, -v20
	v_fmac_f32_e32 v22, v31, v28
	v_sub_f32_e32 v30, v21, v18
	v_add_f32_e32 v18, v20, v22
	v_sub_f32_e32 v21, v19, v18
	v_pk_add_f32 v[24:25], v[18:19], v[20:21] neg_lo:[0,1] neg_hi:[0,1]
	v_mov_b32_e32 v23, v18
	v_pk_add_f32 v[18:19], v[24:25], v[22:23] neg_lo:[0,1] neg_hi:[0,1]
	v_cmp_neq_f32_e32 vcc, s10, v14
	v_add_f32_e32 v19, v30, v19
	v_add_f32_e32 v18, v18, v19
	v_add_f32_e32 v19, v21, v18
	v_mul_f32_e32 v30, v29, v19
	v_mul_f32_e32 v20, v27, v30
	v_fma_f32 v22, v30, v27, -v20
	v_fmac_f32_e32 v22, v30, v28
	v_sub_f32_e32 v21, v21, v19
	v_add_f32_e32 v27, v18, v21
	v_add_f32_e32 v18, v20, v22
	v_sub_f32_e32 v21, v19, v18
	v_pk_add_f32 v[24:25], v[18:19], v[20:21] neg_lo:[0,1] neg_hi:[0,1]
	v_mov_b32_e32 v23, v18
	v_pk_add_f32 v[18:19], v[24:25], v[22:23] neg_lo:[0,1] neg_hi:[0,1]
	s_nop 0
	v_add_f32_e32 v19, v27, v19
	v_add_f32_e32 v18, v18, v19
	v_add_f32_e32 v19, v31, v30
	v_add_f32_e32 v18, v21, v18
	v_sub_f32_e32 v20, v19, v31
	v_mul_f32_e32 v18, v29, v18
	v_sub_f32_e32 v20, v30, v20
	v_add_f32_e32 v20, v20, v18
	v_add_f32_e32 v22, v19, v20
	v_mul_f32_e32 v23, v22, v22
	v_fmamk_f32 v18, v23, 0x3e9b6dac, v175
	v_fmaak_f32 v151, v23, v18, 0x3f2aaada
	v_cvt_f32_i32_e32 v18, v26
	v_sub_f32_e32 v19, v22, v19
	v_sub_f32_e32 v19, v20, v19
	v_ldexp_f32 v24, v19, 1
	v_mul_f32_e32 v19, v22, v23
	v_ldexp_f32 v21, v22, 1
	v_pk_mul_f32 v[22:23], v[18:19], v[150:151]
	s_nop 0
	v_fma_f32 v20, v18, s93, -v22
	v_fmac_f32_e32 v20, 0xb102e308, v18
	v_pk_add_f32 v[18:19], v[22:23], v[20:21]
	s_nop 0
	v_sub_f32_e32 v21, v19, v21
	v_sub_f32_e32 v21, v23, v21
	v_add_f32_e32 v25, v24, v21
	v_mov_b32_e32 v24, v22
	v_pk_add_f32 v[22:23], v[18:19], v[22:23] neg_lo:[0,1] neg_hi:[0,1]
	v_pk_add_f32 v[26:27], v[18:19], v[24:25]
	v_mov_b32_e32 v21, v18
	v_mov_b32_e32 v23, v27
	v_pk_add_f32 v[28:29], v[20:21], v[22:23] neg_lo:[0,1] neg_hi:[0,1]
	v_pk_add_f32 v[20:21], v[20:21], v[22:23]
	v_mov_b32_e32 v24, v25
	v_pk_add_f32 v[22:23], v[20:21], v[18:19] op_sel:[1,0] op_sel_hi:[0,1] neg_lo:[0,1] neg_hi:[0,1]
	v_pk_add_f32 v[30:31], v[26:27], v[22:23] op_sel_hi:[1,0] neg_lo:[0,1] neg_hi:[0,1]
	v_mov_b32_e32 v26, v27
	v_mov_b32_e32 v27, v21
	v_pk_mov_b32 v[22:23], v[18:19], v[22:23] op_sel:[1,0]
	v_mov_b32_e32 v25, v18
	v_pk_add_f32 v[22:23], v[26:27], v[22:23] neg_lo:[0,1] neg_hi:[0,1]
	v_mov_b32_e32 v30, v28
	v_pk_add_f32 v[18:19], v[24:25], v[22:23] neg_lo:[0,1] neg_hi:[0,1]
	v_mov_b32_e32 v29, v21
	v_pk_add_f32 v[22:23], v[30:31], v[18:19]
	s_nop 0
	v_pk_add_f32 v[24:25], v[22:23], v[22:23] op_sel:[0,1] op_sel_hi:[1,0]
	s_nop 0
	v_pk_add_f32 v[20:21], v[20:21], v[24:25] op_sel:[1,0] op_sel_hi:[0,1]
	v_mov_b32_e32 v23, v20
	v_pk_add_f32 v[26:27], v[22:23], v[28:29] neg_lo:[0,1] neg_hi:[0,1]
	v_mov_b32_e32 v19, v24
	v_sub_f32_e32 v21, v22, v26
	v_pk_add_f32 v[18:19], v[18:19], v[26:27] neg_lo:[0,1] neg_hi:[0,1]
	v_sub_f32_e32 v21, v28, v21
	v_add_f32_e32 v18, v18, v21
	v_add_f32_e32 v18, v18, v19
	v_add_f32_e32 v18, v20, v18
	v_cndmask_b32_e32 v18, v178, v18, vcc
	v_cmp_ngt_f32_e32 vcc, -1.0, v14
	s_nop 1
	v_cndmask_b32_e32 v18, v179, v18, vcc
	v_cmp_neq_f32_e32 vcc, -1.0, v14
	s_nop 1
	v_cndmask_b32_e32 v18, v180, v18, vcc
	v_cmp_lt_f32_e64 vcc, |v14|, s11
	s_nop 1
	v_cndmask_b32_e32 v14, v18, v14, vcc

;     __device__ __forceinline__ void operator()(pg8::Acc& acc, const pg8::Unit& u, int wr, int wc, int fr, int fq) const {
;     ...
;         if (pn == 26 && wc == 0 && fq < 2) {
;             const f32x4 db = *(const f32x4*)(dtbias + 4 * fq);
; #pragma unroll
;             for (int ai = 0; ai < 2; ++ai)
; #pragma unroll
;                 for (int m = 0; m < 4; ++m) { const int row = rl0 + ai * 128 + m * 16; f32x4 v = acc[ai][0][m][0] + db;
; #pragma unroll
;                     for (int e = 0; e < 4; ++e) v[e] = (v[e] > 20.f) ? v[e] : log1pf(__expf(v[e]));
;                     *(f32x4*)(DT + (r0 + row) * 8 + 4 * fq) = v; }
;         }
.LBB0_385:
	s_or_b64 exec, exec, s[34:35]
	v_lshlrev_b64 v[18:19], 5, v[154:155]
	v_lshl_add_u64 v[18:19], s[8:9], 0, v[18:19]
	v_pk_add_f32 v[10:11], v[10:11], v[34:35]
	v_lshl_add_u64 v[20:21], v[18:19], 0, v[134:135]
	v_cmp_nlt_f32_e32 vcc, s33, v10
	global_store_dwordx4 v[20:21], v[14:17], off sc1
	s_and_saveexec_b64 s[8:9], vcc
	s_cbranch_execz .LBB0_387
	v_mul_f32_e32 v10, 0x3fb8aa3b, v10
	v_exp_f32_e32 v10, v10
	s_nop 0
	v_add_f32_e32 v16, 1.0, v10
	v_frexp_mant_f32_e32 v20, v16
	v_cvt_f64_f32_e32 v[14:15], v16
	v_frexp_exp_i32_f64_e32 v14, v[14:15]
	v_cmp_gt_f32_e32 vcc, s92, v20
	v_add_f32_e32 v17, -1.0, v16
	v_sub_f32_e32 v21, v17, v16
	v_subbrev_co_u32_e32 v24, vcc, 0, v14, vcc
	v_sub_u32_e32 v14, 0, v24
	v_sub_f32_e32 v17, v10, v17
	v_add_f32_e32 v21, 1.0, v21
	v_ldexp_f32 v15, v16, v14
	v_add_f32_e32 v17, v17, v21
	v_add_f32_e32 v16, -1.0, v15
	v_add_f32_e32 v20, 1.0, v15
	v_ldexp_f32 v14, v17, v14
	v_add_f32_e32 v17, 1.0, v16
	v_add_f32_e32 v21, -1.0, v20
	v_sub_f32_e32 v17, v15, v17
	v_sub_f32_e32 v15, v15, v21
	v_add_f32_e32 v17, v14, v17
	v_add_f32_e32 v14, v14, v15
	v_add_f32_e32 v25, v20, v14
	v_rcp_f32_e32 v27, v25
	v_sub_f32_e32 v15, v25, v20
	v_sub_f32_e32 v26, v14, v15
	v_add_f32_e32 v15, v16, v17
	v_mul_f32_e32 v29, v15, v27
	v_sub_f32_e32 v14, v15, v16
	v_mul_f32_e32 v16, v25, v29
	v_fma_f32 v20, v29, v25, -v16
	v_fmac_f32_e32 v20, v29, v26
	v_sub_f32_e32 v28, v17, v14
	v_add_f32_e32 v14, v16, v20
	v_sub_f32_e32 v17, v15, v14
	v_pk_add_f32 v[22:23], v[14:15], v[16:17] neg_lo:[0,1] neg_hi:[0,1]
	v_mov_b32_e32 v21, v14
	v_pk_add_f32 v[14:15], v[22:23], v[20:21] neg_lo:[0,1] neg_hi:[0,1]
	v_cmp_neq_f32_e32 vcc, s10, v10
	v_add_f32_e32 v15, v28, v15
	v_add_f32_e32 v14, v14, v15
	v_add_f32_e32 v15, v17, v14
	v_mul_f32_e32 v28, v27, v15
	v_mul_f32_e32 v16, v25, v28
	v_fma_f32 v20, v28, v25, -v16
	v_fmac_f32_e32 v20, v28, v26
	v_sub_f32_e32 v17, v17, v15
	v_add_f32_e32 v25, v14, v17
	v_add_f32_e32 v14, v16, v20
	v_sub_f32_e32 v17, v15, v14
	v_pk_add_f32 v[22:23], v[14:15], v[16:17] neg_lo:[0,1] neg_hi:[0,1]
	v_mov_b32_e32 v21, v14
	v_pk_add_f32 v[14:15], v[22:23], v[20:21] neg_lo:[0,1] neg_hi:[0,1]
	s_nop 0
	v_add_f32_e32 v15, v25, v15
	v_add_f32_e32 v14, v14, v15
	v_add_f32_e32 v15, v29, v28
	v_add_f32_e32 v14, v17, v14
	v_sub_f32_e32 v16, v15, v29
	v_mul_f32_e32 v14, v27, v14
	v_sub_f32_e32 v16, v28, v16
	v_add_f32_e32 v16, v16, v14
	v_add_f32_e32 v20, v15, v16
	v_mul_f32_e32 v21, v20, v20
	v_fmamk_f32 v14, v21, 0x3e9b6dac, v175
	v_fmaak_f32 v151, v21, v14, 0x3f2aaada
	v_cvt_f32_i32_e32 v14, v24
	v_sub_f32_e32 v15, v20, v15
	v_sub_f32_e32 v15, v16, v15
	v_ldexp_f32 v22, v15, 1
	v_mul_f32_e32 v15, v20, v21
	v_ldexp_f32 v17, v20, 1
	v_pk_mul_f32 v[20:21], v[14:15], v[150:151]
	s_nop 0
	v_fma_f32 v16, v14, s93, -v20
	v_fmac_f32_e32 v16, 0xb102e308, v14
	v_pk_add_f32 v[14:15], v[20:21], v[16:17]
	s_nop 0
	v_sub_f32_e32 v17, v15, v17
	v_sub_f32_e32 v17, v21, v17
	v_add_f32_e32 v23, v22, v17
	v_mov_b32_e32 v22, v20
	v_pk_add_f32 v[20:21], v[14:15], v[20:21] neg_lo:[0,1] neg_hi:[0,1]
	v_pk_add_f32 v[24:25], v[14:15], v[22:23]
	v_mov_b32_e32 v17, v14
	v_mov_b32_e32 v21, v25
	v_pk_add_f32 v[26:27], v[16:17], v[20:21] neg_lo:[0,1] neg_hi:[0,1]
	v_pk_add_f32 v[16:17], v[16:17], v[20:21]
	v_mov_b32_e32 v22, v23
	v_pk_add_f32 v[20:21], v[16:17], v[14:15] op_sel:[1,0] op_sel_hi:[0,1] neg_lo:[0,1] neg_hi:[0,1]
	v_pk_add_f32 v[28:29], v[24:25], v[20:21] op_sel_hi:[1,0] neg_lo:[0,1] neg_hi:[0,1]
	v_mov_b32_e32 v24, v25
	v_mov_b32_e32 v25, v17
	v_pk_mov_b32 v[20:21], v[14:15], v[20:21] op_sel:[1,0]
	v_mov_b32_e32 v23, v14
	v_pk_add_f32 v[20:21], v[24:25], v[20:21] neg_lo:[0,1] neg_hi:[0,1]
	v_mov_b32_e32 v28, v26
	v_pk_add_f32 v[14:15], v[22:23], v[20:21] neg_lo:[0,1] neg_hi:[0,1]
	v_mov_b32_e32 v27, v17
	v_pk_add_f32 v[20:21], v[28:29], v[14:15]
	s_nop 0
	v_pk_add_f32 v[22:23], v[20:21], v[20:21] op_sel:[0,1] op_sel_hi:[1,0]
	s_nop 0
	v_pk_add_f32 v[16:17], v[16:17], v[22:23] op_sel:[1,0] op_sel_hi:[0,1]
	v_mov_b32_e32 v21, v16
	v_pk_add_f32 v[24:25], v[20:21], v[26:27] neg_lo:[0,1] neg_hi:[0,1]
	v_mov_b32_e32 v15, v22
	v_sub_f32_e32 v17, v20, v24
	v_pk_add_f32 v[14:15], v[14:15], v[24:25] neg_lo:[0,1] neg_hi:[0,1]
	v_sub_f32_e32 v17, v26, v17
	v_add_f32_e32 v14, v14, v17
	v_add_f32_e32 v14, v14, v15
	v_add_f32_e32 v14, v16, v14
	v_cndmask_b32_e32 v14, v178, v14, vcc
	v_cmp_ngt_f32_e32 vcc, -1.0, v10
	s_nop 1
	v_cndmask_b32_e32 v14, v179, v14, vcc
	v_cmp_neq_f32_e32 vcc, -1.0, v10
	s_nop 1
	v_cndmask_b32_e32 v14, v180, v14, vcc
	v_cmp_lt_f32_e64 vcc, |v10|, s11
	s_nop 1
	v_cndmask_b32_e32 v10, v14, v10, vcc

;     __device__ __forceinline__ void operator()(pg8::Acc& acc, const pg8::Unit& u, int wr, int wc, int fr, int fq) const {
;     ...
;         if (pn == 26 && wc == 0 && fq < 2) {
;             const f32x4 db = *(const f32x4*)(dtbias + 4 * fq);
; #pragma unroll
;             for (int ai = 0; ai < 2; ++ai)
; #pragma unroll
;                 for (int m = 0; m < 4; ++m) { const int row = rl0 + ai * 128 + m * 16; f32x4 v = acc[ai][0][m][0] + db;
; #pragma unroll
;                     for (int e = 0; e < 4; ++e) v[e] = (v[e] > 20.f) ? v[e] : log1pf(__expf(v[e]));
;                     *(f32x4*)(DT + (r0 + row) * 8 + 4 * fq) = v; }
;         }
.LBB0_391:
	s_or_b64 exec, exec, s[8:9]
	v_pk_add_f32 v[6:7], v[6:7], v[34:35]
	v_lshl_add_u64 v[14:15], v[18:19], 0, v[134:135]
	v_cmp_nlt_f32_e32 vcc, s33, v6
	global_store_dwordx4 v[14:15], v[10:13], off offset:512 sc1
	s_and_saveexec_b64 s[8:9], vcc
	s_cbranch_execz .LBB0_393
	v_mul_f32_e32 v6, 0x3fb8aa3b, v6
	v_exp_f32_e32 v6, v6
	s_nop 0
	v_add_f32_e32 v12, 1.0, v6
	v_frexp_mant_f32_e32 v14, v12
	v_cvt_f64_f32_e32 v[10:11], v12
	v_frexp_exp_i32_f64_e32 v10, v[10:11]
	v_cmp_gt_f32_e32 vcc, s92, v14
	v_add_f32_e32 v13, -1.0, v12
	v_sub_f32_e32 v15, v13, v12
	v_subbrev_co_u32_e32 v20, vcc, 0, v10, vcc
	v_sub_u32_e32 v10, 0, v20
	v_sub_f32_e32 v13, v6, v13
	v_add_f32_e32 v15, 1.0, v15
	v_ldexp_f32 v11, v12, v10
	v_add_f32_e32 v13, v13, v15
	v_add_f32_e32 v12, -1.0, v11
	v_add_f32_e32 v14, 1.0, v11
	v_ldexp_f32 v10, v13, v10
	v_add_f32_e32 v13, 1.0, v12
	v_add_f32_e32 v15, -1.0, v14
	v_sub_f32_e32 v13, v11, v13
	v_sub_f32_e32 v11, v11, v15
	v_add_f32_e32 v13, v10, v13
	v_add_f32_e32 v10, v10, v11
	v_add_f32_e32 v21, v14, v10
	v_rcp_f32_e32 v23, v21
	v_sub_f32_e32 v11, v21, v14
	v_sub_f32_e32 v22, v10, v11
	v_add_f32_e32 v11, v12, v13
	v_mul_f32_e32 v25, v11, v23
	v_sub_f32_e32 v10, v11, v12
	v_mul_f32_e32 v12, v21, v25
	v_fma_f32 v14, v25, v21, -v12
	v_fmac_f32_e32 v14, v25, v22
	v_sub_f32_e32 v24, v13, v10
	v_add_f32_e32 v10, v12, v14
	v_sub_f32_e32 v13, v11, v10
	v_pk_add_f32 v[16:17], v[10:11], v[12:13] neg_lo:[0,1] neg_hi:[0,1]
	v_mov_b32_e32 v15, v10
	v_pk_add_f32 v[10:11], v[16:17], v[14:15] neg_lo:[0,1] neg_hi:[0,1]
	v_cmp_neq_f32_e32 vcc, s10, v6
	v_add_f32_e32 v11, v24, v11
	v_add_f32_e32 v10, v10, v11
	v_add_f32_e32 v11, v13, v10
	v_mul_f32_e32 v24, v23, v11
	v_mul_f32_e32 v12, v21, v24
	v_fma_f32 v14, v24, v21, -v12
	v_fmac_f32_e32 v14, v24, v22
	v_sub_f32_e32 v13, v13, v11
	v_add_f32_e32 v21, v10, v13
	v_add_f32_e32 v10, v12, v14
	v_sub_f32_e32 v13, v11, v10
	v_pk_add_f32 v[16:17], v[10:11], v[12:13] neg_lo:[0,1] neg_hi:[0,1]
	v_mov_b32_e32 v15, v10
	v_pk_add_f32 v[10:11], v[16:17], v[14:15] neg_lo:[0,1] neg_hi:[0,1]
	s_nop 0
	v_add_f32_e32 v11, v21, v11
	v_add_f32_e32 v10, v10, v11
	v_add_f32_e32 v11, v25, v24
	v_add_f32_e32 v10, v13, v10
	v_sub_f32_e32 v12, v11, v25
	v_mul_f32_e32 v10, v23, v10
	v_sub_f32_e32 v12, v24, v12
	v_add_f32_e32 v12, v12, v10
	v_add_f32_e32 v14, v11, v12
	v_mul_f32_e32 v15, v14, v14
	v_fmamk_f32 v10, v15, 0x3e9b6dac, v175
	v_fmaak_f32 v151, v15, v10, 0x3f2aaada
	v_cvt_f32_i32_e32 v10, v20
	v_sub_f32_e32 v11, v14, v11
	v_sub_f32_e32 v11, v12, v11
	v_ldexp_f32 v16, v11, 1
	v_mul_f32_e32 v11, v14, v15
	v_ldexp_f32 v13, v14, 1
	v_pk_mul_f32 v[14:15], v[10:11], v[150:151]
	s_nop 0
	v_fma_f32 v12, v10, s93, -v14
	v_fmac_f32_e32 v12, 0xb102e308, v10
	v_pk_add_f32 v[10:11], v[14:15], v[12:13]
	s_nop 0
	v_sub_f32_e32 v13, v11, v13
	v_sub_f32_e32 v13, v15, v13
	v_add_f32_e32 v17, v16, v13
	v_mov_b32_e32 v16, v14
	v_pk_add_f32 v[14:15], v[10:11], v[14:15] neg_lo:[0,1] neg_hi:[0,1]
	v_pk_add_f32 v[20:21], v[10:11], v[16:17]
	v_mov_b32_e32 v13, v10
	v_mov_b32_e32 v15, v21
	v_pk_add_f32 v[22:23], v[12:13], v[14:15] neg_lo:[0,1] neg_hi:[0,1]
	v_pk_add_f32 v[12:13], v[12:13], v[14:15]
	v_mov_b32_e32 v16, v17
	v_pk_add_f32 v[14:15], v[12:13], v[10:11] op_sel:[1,0] op_sel_hi:[0,1] neg_lo:[0,1] neg_hi:[0,1]
	v_pk_add_f32 v[24:25], v[20:21], v[14:15] op_sel_hi:[1,0] neg_lo:[0,1] neg_hi:[0,1]
	v_mov_b32_e32 v20, v21
	v_mov_b32_e32 v21, v13
	v_pk_mov_b32 v[14:15], v[10:11], v[14:15] op_sel:[1,0]
	v_mov_b32_e32 v17, v10
	v_pk_add_f32 v[14:15], v[20:21], v[14:15] neg_lo:[0,1] neg_hi:[0,1]
	v_mov_b32_e32 v24, v22
	v_pk_add_f32 v[10:11], v[16:17], v[14:15] neg_lo:[0,1] neg_hi:[0,1]
	v_mov_b32_e32 v23, v13
	v_pk_add_f32 v[14:15], v[24:25], v[10:11]
	s_nop 0
	v_pk_add_f32 v[16:17], v[14:15], v[14:15] op_sel:[0,1] op_sel_hi:[1,0]
	s_nop 0
	v_pk_add_f32 v[12:13], v[12:13], v[16:17] op_sel:[1,0] op_sel_hi:[0,1]
	v_mov_b32_e32 v15, v12
	v_pk_add_f32 v[20:21], v[14:15], v[22:23] neg_lo:[0,1] neg_hi:[0,1]
	v_mov_b32_e32 v11, v16
	v_sub_f32_e32 v13, v14, v20
	v_pk_add_f32 v[10:11], v[10:11], v[20:21] neg_lo:[0,1] neg_hi:[0,1]
	v_sub_f32_e32 v13, v22, v13
	v_add_f32_e32 v10, v10, v13
	v_add_f32_e32 v10, v10, v11
	v_add_f32_e32 v10, v12, v10
	v_cndmask_b32_e32 v10, v178, v10, vcc
	v_cmp_ngt_f32_e32 vcc, -1.0, v6
	s_nop 1
	v_cndmask_b32_e32 v10, v179, v10, vcc
	v_cmp_neq_f32_e32 vcc, -1.0, v6
	s_nop 1
	v_cndmask_b32_e32 v10, v180, v10, vcc
	v_cmp_lt_f32_e64 vcc, |v6|, s11
	s_nop 1
	v_cndmask_b32_e32 v6, v10, v6, vcc

;     __device__ __forceinline__ void operator()(pg8::Acc& acc, const pg8::Unit& u, int wr, int wc, int fr, int fq) const {
;     ...
;         if (pn == 26 && wc == 0 && fq < 2) {
;             const f32x4 db = *(const f32x4*)(dtbias + 4 * fq);
; #pragma unroll
;             for (int ai = 0; ai < 2; ++ai)
; #pragma unroll
;                 for (int m = 0; m < 4; ++m) { const int row = rl0 + ai * 128 + m * 16; f32x4 v = acc[ai][0][m][0] + db;
; #pragma unroll
;                     for (int e = 0; e < 4; ++e) v[e] = (v[e] > 20.f) ? v[e] : log1pf(__expf(v[e]));
;                     *(f32x4*)(DT + (r0 + row) * 8 + 4 * fq) = v; }
;         }
.LBB0_397:
	s_or_b64 exec, exec, s[8:9]
	v_pk_add_f32 v[2:3], v[2:3], v[34:35]
	v_lshl_add_u64 v[10:11], v[18:19], 0, v[134:135]
	v_cmp_nlt_f32_e32 vcc, s33, v2
	global_store_dwordx4 v[10:11], v[6:9], off offset:1024 sc1
	s_and_saveexec_b64 s[8:9], vcc
	s_cbranch_execz .LBB0_399
	v_mul_f32_e32 v2, 0x3fb8aa3b, v2
	v_exp_f32_e32 v2, v2
	s_nop 0
	v_add_f32_e32 v8, 1.0, v2
	v_frexp_mant_f32_e32 v10, v8
	v_cvt_f64_f32_e32 v[6:7], v8
	v_frexp_exp_i32_f64_e32 v6, v[6:7]
	v_cmp_gt_f32_e32 vcc, s92, v10
	v_add_f32_e32 v9, -1.0, v8
	v_sub_f32_e32 v11, v9, v8
	v_subbrev_co_u32_e32 v14, vcc, 0, v6, vcc
	v_sub_u32_e32 v6, 0, v14
	v_sub_f32_e32 v9, v2, v9
	v_add_f32_e32 v11, 1.0, v11
	v_ldexp_f32 v7, v8, v6
	v_add_f32_e32 v9, v9, v11
	v_add_f32_e32 v8, -1.0, v7
	v_add_f32_e32 v10, 1.0, v7
	v_ldexp_f32 v6, v9, v6
	v_add_f32_e32 v9, 1.0, v8
	v_add_f32_e32 v11, -1.0, v10
	v_sub_f32_e32 v9, v7, v9
	v_sub_f32_e32 v7, v7, v11
	v_add_f32_e32 v9, v6, v9
	v_add_f32_e32 v6, v6, v7
	v_add_f32_e32 v15, v10, v6
	v_rcp_f32_e32 v17, v15
	v_sub_f32_e32 v7, v15, v10
	v_sub_f32_e32 v16, v6, v7
	v_add_f32_e32 v7, v8, v9
	v_mul_f32_e32 v21, v7, v17
	v_sub_f32_e32 v6, v7, v8
	v_mul_f32_e32 v8, v15, v21
	v_fma_f32 v10, v21, v15, -v8
	v_fmac_f32_e32 v10, v21, v16
	v_sub_f32_e32 v20, v9, v6
	v_add_f32_e32 v6, v8, v10
	v_sub_f32_e32 v9, v7, v6
	v_pk_add_f32 v[12:13], v[6:7], v[8:9] neg_lo:[0,1] neg_hi:[0,1]
	v_mov_b32_e32 v11, v6
	v_pk_add_f32 v[6:7], v[12:13], v[10:11] neg_lo:[0,1] neg_hi:[0,1]
	v_cmp_neq_f32_e32 vcc, s10, v2
	v_add_f32_e32 v7, v20, v7
	v_add_f32_e32 v6, v6, v7
	v_add_f32_e32 v7, v9, v6
	v_mul_f32_e32 v20, v17, v7
	v_mul_f32_e32 v8, v15, v20
	v_fma_f32 v10, v20, v15, -v8
	v_fmac_f32_e32 v10, v20, v16
	v_sub_f32_e32 v9, v9, v7
	v_add_f32_e32 v15, v6, v9
	v_add_f32_e32 v6, v8, v10
	v_sub_f32_e32 v9, v7, v6
	v_pk_add_f32 v[12:13], v[6:7], v[8:9] neg_lo:[0,1] neg_hi:[0,1]
	v_mov_b32_e32 v11, v6
	v_pk_add_f32 v[6:7], v[12:13], v[10:11] neg_lo:[0,1] neg_hi:[0,1]
	s_nop 0
	v_add_f32_e32 v7, v15, v7
	v_add_f32_e32 v6, v6, v7
	v_add_f32_e32 v7, v21, v20
	v_add_f32_e32 v6, v9, v6
	v_sub_f32_e32 v8, v7, v21
	v_mul_f32_e32 v6, v17, v6
	v_sub_f32_e32 v8, v20, v8
	v_add_f32_e32 v8, v8, v6
	v_add_f32_e32 v10, v7, v8
	v_mul_f32_e32 v11, v10, v10
	v_fmamk_f32 v6, v11, 0x3e9b6dac, v175
	v_fmaak_f32 v151, v11, v6, 0x3f2aaada
	v_cvt_f32_i32_e32 v6, v14
	v_sub_f32_e32 v7, v10, v7
	v_sub_f32_e32 v7, v8, v7
	v_ldexp_f32 v12, v7, 1
	v_mul_f32_e32 v7, v10, v11
	v_ldexp_f32 v9, v10, 1
	v_pk_mul_f32 v[10:11], v[6:7], v[150:151]
	s_nop 0
	v_fma_f32 v8, v6, s93, -v10
	v_fmac_f32_e32 v8, 0xb102e308, v6
	v_pk_add_f32 v[6:7], v[10:11], v[8:9]
	s_nop 0
	v_sub_f32_e32 v9, v7, v9
	v_sub_f32_e32 v9, v11, v9
	v_add_f32_e32 v13, v12, v9
	v_mov_b32_e32 v12, v10
	v_pk_add_f32 v[10:11], v[6:7], v[10:11] neg_lo:[0,1] neg_hi:[0,1]
	v_pk_add_f32 v[14:15], v[6:7], v[12:13]
	v_mov_b32_e32 v9, v6
	v_mov_b32_e32 v11, v15
	v_pk_add_f32 v[16:17], v[8:9], v[10:11] neg_lo:[0,1] neg_hi:[0,1]
	v_pk_add_f32 v[8:9], v[8:9], v[10:11]
	v_mov_b32_e32 v12, v13
	v_pk_add_f32 v[10:11], v[8:9], v[6:7] op_sel:[1,0] op_sel_hi:[0,1] neg_lo:[0,1] neg_hi:[0,1]
	v_pk_add_f32 v[20:21], v[14:15], v[10:11] op_sel_hi:[1,0] neg_lo:[0,1] neg_hi:[0,1]
	v_mov_b32_e32 v14, v15
	v_mov_b32_e32 v15, v9
	v_pk_mov_b32 v[10:11], v[6:7], v[10:11] op_sel:[1,0]
	v_mov_b32_e32 v13, v6
	v_pk_add_f32 v[10:11], v[14:15], v[10:11] neg_lo:[0,1] neg_hi:[0,1]
	v_mov_b32_e32 v20, v16
	v_pk_add_f32 v[6:7], v[12:13], v[10:11] neg_lo:[0,1] neg_hi:[0,1]
	v_mov_b32_e32 v17, v9
	v_pk_add_f32 v[10:11], v[20:21], v[6:7]
	s_nop 0
	v_pk_add_f32 v[12:13], v[10:11], v[10:11] op_sel:[0,1] op_sel_hi:[1,0]
	s_nop 0
	v_pk_add_f32 v[8:9], v[8:9], v[12:13] op_sel:[1,0] op_sel_hi:[0,1]
	v_mov_b32_e32 v11, v8
	v_pk_add_f32 v[14:15], v[10:11], v[16:17] neg_lo:[0,1] neg_hi:[0,1]
	v_mov_b32_e32 v7, v12
	v_sub_f32_e32 v9, v10, v14
	v_pk_add_f32 v[6:7], v[6:7], v[14:15] neg_lo:[0,1] neg_hi:[0,1]
	v_sub_f32_e32 v9, v16, v9
	v_add_f32_e32 v6, v6, v9
	v_add_f32_e32 v6, v6, v7
	v_add_f32_e32 v6, v8, v6
	v_cndmask_b32_e32 v6, v178, v6, vcc
	v_cmp_ngt_f32_e32 vcc, -1.0, v2
	s_nop 1
	v_cndmask_b32_e32 v6, v179, v6, vcc
	v_cmp_neq_f32_e32 vcc, -1.0, v2
	s_nop 1
	v_cndmask_b32_e32 v6, v180, v6, vcc
	v_cmp_lt_f32_e64 vcc, |v2|, s11
	s_nop 1
	v_cndmask_b32_e32 v2, v6, v2, vcc

;     __device__ __forceinline__ void operator()(pg8::Acc& acc, const pg8::Unit& u, int wr, int wc, int fr, int fq) const {
;     ...
;         if (pn == 26 && wc == 0 && fq < 2) {
;             const f32x4 db = *(const f32x4*)(dtbias + 4 * fq);
; #pragma unroll
;             for (int ai = 0; ai < 2; ++ai)
; #pragma unroll
;                 for (int m = 0; m < 4; ++m) { const int row = rl0 + ai * 128 + m * 16; f32x4 v = acc[ai][0][m][0] + db;
; #pragma unroll
;                     for (int e = 0; e < 4; ++e) v[e] = (v[e] > 20.f) ? v[e] : log1pf(__expf(v[e]));
;                     *(f32x4*)(DT + (r0 + row) * 8 + 4 * fq) = v; }
;         }
.LBB0_403:
	s_or_b64 exec, exec, s[8:9]
	v_lshl_add_u64 v[6:7], v[18:19], 0, v[134:135]
	global_store_dwordx4 v[6:7], v[2:5], off offset:1536 sc1

; #define E5_LOAD(dst, b) do { _Pragma("unroll") for (int mm = 0; mm < 2; ++mm) { const float* xr = xb + (size_t)(rl0 + ((b) >> 1) * 128 + (((b) & 1) * 2 + mm) * 16) * DM; \
;         _Pragma("unroll") for (int bj = 0; bj < 2; ++bj) _Pragma("unroll") for (int n = 0; n < 2; ++n) dst[mm][bj][n] = *(const f32x4*)(xr + bj * 128 + n * 16); } } while (0)
; #define E5_STORE(src, b) do { _Pragma("unroll") for (int mm = 0; mm < 2; ++mm) { float* orow = ob + (size_t)(rl0 + ((b) >> 1) * 128 + (((b) & 1) * 2 + mm) * 16) * DM; \
;         _Pragma("unroll") for (int bj = 0; bj < 2; ++bj) _Pragma("unroll") for (int n = 0; n < 2; ++n) *(f32x4*)(orow + bj * 128 + n * 16) = src[mm][bj][n] + acc[(b) >> 1][bj][((b) & 1) * 2 + mm][n]; } } while (0)
;     __device__ __forceinline__ void operator()(pg8::Acc& acc, const pg8::Unit& u, int wr, int wc, int fr, int fq) const {
;         int rl0 = wr * 64 + fr, cl0 = u.pn * 256 + wc * 32 + 4 * fq;
;         asm volatile("" : "+v"(rl0), "+v"(cl0));
;         const float* xb = xp + (size_t)u.pm * 256 * DM + cl0; float* ob = out + O_YP + (size_t)u.pm * 256 * DM + cl0;
;         f32x4 xa[2][2][2], xc[2][2][2];
;     ...
;         E5_LOAD(xa, 0); E5_LOAD(xc, 1);
;         E5_STORE(xa, 0); E5_LOAD(xa, 2);
;         E5_STORE(xc, 1); E5_LOAD(xc, 3);
;         E5_STORE(xa, 2); E5_STORE(xc, 3);
;     ...
;     }
.LBB0_1215:
	v_lshl_or_b32 v134, s66, 8, v158
	v_mov_b32_e32 v4, v156
	s_lshl_b64 s[2:3], s[40:41], 21
	s_add_u32 s4, s36, s2
	v_ashrrev_i32_e32 v135, 31, v134
	s_addc_u32 s5, s37, s3
	v_lshlrev_b64 v[154:155], 2, v[134:135]
	v_ashrrev_i32_e32 v5, 31, v4
	v_lshl_add_u64 v[152:153], s[4:5], 0, v[154:155]
	v_lshlrev_b64 v[218:219], 13, v[4:5]
	v_lshl_add_u64 v[134:135], v[152:153], 0, v[218:219]
	v_lshl_add_u64 v[220:221], v[218:219], 0, s[20:21]
	global_load_dwordx4 v[162:165], v[134:135], off
	global_load_dwordx4 v[166:169], v[134:135], off offset:64
	global_load_dwordx4 v[170:173], v[134:135], off offset:512
	global_load_dwordx4 v[174:177], v[134:135], off offset:576
	v_lshl_add_u64 v[134:135], v[152:153], 0, v[220:221]
	global_load_dwordx4 v[178:181], v[134:135], off
	global_load_dwordx4 v[182:185], v[134:135], off offset:64
	global_load_dwordx4 v[186:189], v[134:135], off offset:512
	global_load_dwordx4 v[190:193], v[134:135], off offset:576
	v_add_u32_e32 v134, 32, v4
	v_ashrrev_i32_e32 v135, 31, v134
	v_lshlrev_b64 v[222:223], 13, v[134:135]
	v_lshl_add_u64 v[134:135], v[152:153], 0, v[222:223]
	global_load_dwordx4 v[194:197], v[134:135], off
	global_load_dwordx4 v[198:201], v[134:135], off offset:64
	global_load_dwordx4 v[202:205], v[134:135], off offset:512
	global_load_dwordx4 v[206:209], v[134:135], off offset:576
	v_add_u32_e32 v134, 48, v4
	v_ashrrev_i32_e32 v135, 31, v134
	v_lshlrev_b64 v[224:225], 13, v[134:135]
	v_lshl_add_u64 v[134:135], v[152:153], 0, v[224:225]
	global_load_dwordx4 v[210:213], v[134:135], off
	global_load_dwordx4 v[214:217], v[134:135], off offset:64
	global_load_dwordx4 v[138:141], v[134:135], off offset:512
	s_nop 0
	global_load_dwordx4 v[134:137], v[134:135], off offset:576
	s_add_u32 s2, s88, s2
	s_addc_u32 s3, s89, s3
	v_add_u32_e32 v226, 0xa0, v4
	v_lshl_add_u64 v[154:155], s[2:3], 0, v[154:155]
	v_add_u32_e32 v4, 0xb0, v4
	v_ashrrev_i32_e32 v227, 31, v226
	v_lshl_add_u64 v[228:229], v[218:219], 0, s[22:23]
	v_lshl_add_u64 v[230:231], v[218:219], 0, s[26:27]
	v_lshl_add_u64 v[218:219], v[154:155], 0, v[218:219]
	v_ashrrev_i32_e32 v5, 31, v4
	v_lshlrev_b64 v[226:227], 13, v[226:227]
	v_lshl_add_u64 v[232:233], v[152:153], 0, v[228:229]
	v_lshl_add_u64 v[234:235], v[152:153], 0, v[230:231]
	v_lshl_add_u64 v[220:221], v[154:155], 0, v[220:221]
	v_lshl_add_u64 v[222:223], v[154:155], 0, v[222:223]
	v_lshlrev_b64 v[4:5], 13, v[4:5]
	v_lshl_add_u64 v[236:237], v[152:153], 0, v[226:227]
	v_lshl_add_u64 v[224:225], v[154:155], 0, v[224:225]
	s_andn2_b64 vcc, exec, s[0:1]
	s_mov_b64 s[0:1], -1
	s_waitcnt vmcnt(0)
	v_pk_add_f32 v[132:133], v[132:133], v[164:165]
	v_pk_add_f32 v[130:131], v[130:131], v[162:163]
	v_pk_add_f32 v[128:129], v[128:129], v[168:169]
	v_pk_add_f32 v[126:127], v[126:127], v[166:167]
	v_pk_add_f32 v[120:121], v[120:121], v[172:173]
	v_pk_add_f32 v[118:119], v[118:119], v[170:171]
	v_pk_add_f32 v[112:113], v[112:113], v[176:177]
	v_pk_add_f32 v[110:111], v[110:111], v[174:175]
	v_pk_add_f32 v[124:125], v[124:125], v[180:181]
	v_pk_add_f32 v[122:123], v[122:123], v[178:179]
	v_pk_add_f32 v[116:117], v[116:117], v[184:185]
	v_pk_add_f32 v[114:115], v[114:115], v[182:183]
	v_pk_add_f32 v[104:105], v[104:105], v[188:189]
	v_pk_add_f32 v[102:103], v[102:103], v[186:187]
	v_pk_add_f32 v[96:97], v[96:97], v[192:193]
	v_pk_add_f32 v[94:95], v[94:95], v[190:191]
	v_pk_add_f32 v[108:109], v[108:109], v[196:197]
	v_pk_add_f32 v[106:107], v[106:107], v[194:195]
	global_store_dwordx4 v[218:219], v[130:133], off sc1
	global_store_dwordx4 v[218:219], v[126:129], off offset:64 sc1
	global_store_dwordx4 v[218:219], v[118:121], off offset:512 sc1
	global_store_dwordx4 v[218:219], v[110:113], off offset:576 sc1
	global_store_dwordx4 v[220:221], v[122:125], off sc1
	global_store_dwordx4 v[220:221], v[114:117], off offset:64 sc1
	global_store_dwordx4 v[220:221], v[102:105], off offset:512 sc1
	global_store_dwordx4 v[220:221], v[94:97], off offset:576 sc1
	v_pk_add_f32 v[100:101], v[100:101], v[200:201]
	v_pk_add_f32 v[98:99], v[98:99], v[198:199]
	v_pk_add_f32 v[92:93], v[92:93], v[204:205]
	v_pk_add_f32 v[90:91], v[90:91], v[202:203]
	v_pk_add_f32 v[88:89], v[88:89], v[208:209]
	v_pk_add_f32 v[86:87], v[86:87], v[206:207]
	global_load_dwordx4 v[94:97], v[232:233], off
	global_load_dwordx4 v[102:105], v[232:233], off offset:64
	v_pk_add_f32 v[84:85], v[84:85], v[212:213]
	v_pk_add_f32 v[82:83], v[82:83], v[210:211]
	global_load_dwordx4 v[110:113], v[232:233], off offset:512
	global_load_dwordx4 v[114:117], v[232:233], off offset:576
	v_pk_add_f32 v[80:81], v[80:81], v[216:217]
	v_pk_add_f32 v[78:79], v[78:79], v[214:215]
	global_load_dwordx4 v[118:121], v[234:235], off
	global_load_dwordx4 v[122:125], v[234:235], off offset:64
	v_pk_add_f32 v[76:77], v[76:77], v[140:141]
	v_pk_add_f32 v[74:75], v[74:75], v[138:139]
	global_load_dwordx4 v[126:129], v[234:235], off offset:512
	global_load_dwordx4 v[130:133], v[234:235], off offset:576
	v_pk_add_f32 v[72:73], v[72:73], v[136:137]
	v_pk_add_f32 v[70:71], v[70:71], v[134:135]
	global_store_dwordx4 v[222:223], v[106:109], off sc1
	global_store_dwordx4 v[222:223], v[98:101], off offset:64 sc1
	global_store_dwordx4 v[222:223], v[90:93], off offset:512 sc1
	global_store_dwordx4 v[222:223], v[86:89], off offset:576 sc1
	global_store_dwordx4 v[224:225], v[82:85], off sc1
	global_store_dwordx4 v[224:225], v[78:81], off offset:64 sc1
	global_store_dwordx4 v[224:225], v[74:77], off offset:512 sc1
	global_store_dwordx4 v[224:225], v[70:73], off offset:576 sc1
	v_lshl_add_u64 v[106:107], v[152:153], 0, v[4:5]
	global_load_dwordx4 v[70:73], v[236:237], off
	global_load_dwordx4 v[74:77], v[236:237], off offset:64
	global_load_dwordx4 v[78:81], v[236:237], off offset:512
	global_load_dwordx4 v[82:85], v[236:237], off offset:576
	global_load_dwordx4 v[86:89], v[106:107], off
	global_load_dwordx4 v[90:93], v[106:107], off offset:64
	global_load_dwordx4 v[98:101], v[106:107], off offset:512
	s_nop 0
	global_load_dwordx4 v[106:109], v[106:107], off offset:576
	v_lshl_add_u64 v[134:135], v[154:155], 0, v[228:229]
	v_lshl_add_u64 v[138:139], v[154:155], 0, v[226:227]
	v_lshl_add_u64 v[4:5], v[154:155], 0, v[4:5]
	v_lshl_add_u64 v[136:137], v[154:155], 0, v[230:231]
	s_waitcnt vmcnt(23)
; #define PG8_BAR __builtin_amdgcn_s_barrier()
; #define E5_LOAD(dst, b) do { _Pragma("unroll") for (int mm = 0; mm < 2; ++mm) { const float* xr = xb + (size_t)(rl0 + ((b) >> 1) * 128 + (((b) & 1) * 2 + mm) * 16) * DM; \
;         _Pragma("unroll") for (int bj = 0; bj < 2; ++bj) _Pragma("unroll") for (int n = 0; n < 2; ++n) dst[mm][bj][n] = *(const f32x4*)(xr + bj * 128 + n * 16); } } while (0)
; #define E5_STORE(src, b) do { _Pragma("unroll") for (int mm = 0; mm < 2; ++mm) { float* orow = ob + (size_t)(rl0 + ((b) >> 1) * 128 + (((b) & 1) * 2 + mm) * 16) * DM; \
;         _Pragma("unroll") for (int bj = 0; bj < 2; ++bj) _Pragma("unroll") for (int n = 0; n < 2; ++n) *(f32x4*)(orow + bj * 128 + n * 16) = src[mm][bj][n] + acc[(b) >> 1][bj][((b) & 1) * 2 + mm][n]; } } while (0)
; template <class Epi>
; __device__ __forceinline__ void gemm_phase(LAS unsigned char* lds, const Gemm g, const Order& S, const Epi& E) {
;     ...
;         cur = nxt; cA = nA; cB = nB; ++ui;
;         if (wr == 1) PG8_BAR;
;     __device__ __forceinline__ void operator()(pg8::Acc& acc, const pg8::Unit& u, int wr, int wc, int fr, int fq) const {
;     ...
;         E5_LOAD(xa, 0); E5_LOAD(xc, 1);
;         E5_STORE(xa, 0); E5_LOAD(xa, 2);
;         E5_STORE(xc, 1); E5_LOAD(xc, 3);
;         E5_STORE(xa, 2); E5_STORE(xc, 3);
;     ...
;     }
	v_pk_add_f32 v[68:69], v[68:69], v[96:97]
	v_pk_add_f32 v[66:67], v[66:67], v[94:95]
	s_waitcnt vmcnt(22)
	v_pk_add_f32 v[64:65], v[64:65], v[104:105]
	v_pk_add_f32 v[62:63], v[62:63], v[102:103]
	s_waitcnt vmcnt(21)
	v_pk_add_f32 v[56:57], v[56:57], v[112:113]
	v_pk_add_f32 v[54:55], v[54:55], v[110:111]
	s_waitcnt vmcnt(20)
	v_pk_add_f32 v[48:49], v[48:49], v[116:117]
	v_pk_add_f32 v[46:47], v[46:47], v[114:115]
	s_waitcnt vmcnt(19)
	v_pk_add_f32 v[60:61], v[60:61], v[120:121]
	v_pk_add_f32 v[58:59], v[58:59], v[118:119]
	s_waitcnt vmcnt(18)
	v_pk_add_f32 v[52:53], v[52:53], v[124:125]
	v_pk_add_f32 v[50:51], v[50:51], v[122:123]
	s_waitcnt vmcnt(17)
	v_pk_add_f32 v[44:45], v[44:45], v[128:129]
	v_pk_add_f32 v[42:43], v[42:43], v[126:127]
	s_waitcnt vmcnt(16)
	v_pk_add_f32 v[40:41], v[40:41], v[132:133]
	v_pk_add_f32 v[38:39], v[38:39], v[130:131]
	global_store_dwordx4 v[134:135], v[66:69], off sc1
	global_store_dwordx4 v[134:135], v[62:65], off offset:64 sc1
	global_store_dwordx4 v[134:135], v[54:57], off offset:512 sc1
	global_store_dwordx4 v[134:135], v[46:49], off offset:576 sc1
	global_store_dwordx4 v[136:137], v[58:61], off sc1
	global_store_dwordx4 v[136:137], v[50:53], off offset:64 sc1
	global_store_dwordx4 v[136:137], v[42:45], off offset:512 sc1
	global_store_dwordx4 v[136:137], v[38:41], off offset:576 sc1
	s_waitcnt vmcnt(15)
	v_pk_add_f32 v[36:37], v[36:37], v[72:73]
	v_pk_add_f32 v[34:35], v[34:35], v[70:71]
	s_waitcnt vmcnt(14)
	v_pk_add_f32 v[32:33], v[32:33], v[76:77]
	v_pk_add_f32 v[30:31], v[30:31], v[74:75]
	s_waitcnt vmcnt(8)
	v_pk_add_f32 v[8:9], v[8:9], v[108:109]
	v_pk_add_f32 v[6:7], v[6:7], v[106:107]
	v_pk_add_f32 v[28:29], v[28:29], v[80:81]
	v_pk_add_f32 v[26:27], v[26:27], v[78:79]
	v_pk_add_f32 v[20:21], v[20:21], v[84:85]
	v_pk_add_f32 v[18:19], v[18:19], v[82:83]
	v_pk_add_f32 v[24:25], v[24:25], v[88:89]
	v_pk_add_f32 v[22:23], v[22:23], v[86:87]
	v_pk_add_f32 v[16:17], v[16:17], v[92:93]
	v_pk_add_f32 v[14:15], v[14:15], v[90:91]
	v_pk_add_f32 v[12:13], v[12:13], v[100:101]
	v_pk_add_f32 v[10:11], v[10:11], v[98:99]
	global_store_dwordx4 v[138:139], v[34:37], off sc1
	global_store_dwordx4 v[138:139], v[30:33], off offset:64 sc1
	global_store_dwordx4 v[138:139], v[26:29], off offset:512 sc1
	global_store_dwordx4 v[138:139], v[18:21], off offset:576 sc1
	global_store_dwordx4 v[4:5], v[22:25], off sc1
	global_store_dwordx4 v[4:5], v[14:17], off offset:64 sc1
	global_store_dwordx4 v[4:5], v[10:13], off offset:512 sc1
	global_store_dwordx4 v[4:5], v[6:9], off offset:576 sc1
	s_cbranch_vccnz .LBB0_1202
	s_andn2_b64 vcc, exec, s[6:7]
	s_cbranch_vccnz .LBB0_1201
	s_barrier
	s_branch .LBB0_1201
